# stacked: parity-specialised dilated masks, gate GEMM row statistics via LDS DMA, gate epilogue sigmoid pairs packed
# baseline (speedup 1.0000x reference)
.LBB0_1392:
	s_ashr_i32 s4, s37, 7
	s_mul_hi_i32 s5, s4, 0x55555556
	s_lshr_b32 s12, s5, 31
	s_add_i32 s5, s5, s12
	s_mul_i32 s5, s5, 3
	s_ashr_i32 s0, s37, 5
	s_and_b32 s1, s37, 31
	s_sub_i32 s4, s4, s5
	s_cmp_eq_u32 s4, 0
	s_cselect_b64 s[14:15], -1, 0
	s_cmp_eq_u32 s4, 1
	s_cselect_b64 s[16:17], -1, 0
	s_and_b64 s[4:5], s[16:17], exec
	s_cselect_b32 s12, 2, 4
	s_and_b64 s[4:5], s[14:15], exec
	s_cselect_b32 s4, 0, s12
	s_lshr_b32 s5, 32, s4
	s_sub_i32 s12, 5, s4
	s_add_i32 s5, s5, -1
	v_readfirstlane_b32 s42, v0
	s_lshr_b32 s12, s1, s12
	s_and_b32 s20, s5, s1
	s_ashr_i32 s46, s42, 6
	s_bfe_u32 s92, s42, 0x10006
	s_ashr_i32 s1, s0, 31
	s_lshl_b64 s[18:19], s[0:1], 13
	s_lshl_b32 s0, s20, 8
	s_lshl_b32 s38, s46, 5
	s_add_i32 s38, s38, s0
	v_or_b32_e32 v2, s38, v1
	v_ashrrev_i32_e32 v3, 31, v2
	s_or_b32 s18, s18, s12
	v_lshlrev_b64 v[2:3], s4, v[2:3]
	v_lshl_add_u64 v[108:109], v[2:3], 0, s[18:19]
	v_lshlrev_b64 v[2:3], 7, v[108:109]
	v_lshl_add_u64 v[2:3], v[102:103], 0, v[2:3]
	global_load_dwordx4 v[66:69], v[2:3], off offset:96
	global_load_dwordx4 v[70:73], v[2:3], off offset:64
	global_load_dwordx4 v[74:77], v[2:3], off offset:32
	global_load_dwordx4 v[78:81], v[2:3], off
	s_lshl_b32 s0, s46, 8
	s_add_i32 s39, s0, 0
	s_add_i32 s39, s39, 0x18840
	s_lshl_b64 s[0:1], s[18:19], 7
	s_add_u32 s4, s24, s0
	s_addc_u32 s5, s25, s1
	s_add_u32 s0, s22, s0
	s_addc_u32 s1, s23, s1
	s_lshl_b32 s45, s20, 2
	s_add_i32 s43, s45, -2
	s_cmp_lg_u32 s20, 0
	s_cselect_b32 s12, s43, 0
	s_or_b32 s20, s45, 3
	s_sub_i32 s44, s20, s12
	s_lshl_b64 s[28:29], s[12:13], 6
	s_and_b64 s[40:41], s[16:17], exec
	s_cselect_b32 s20, 8, 10
	s_and_b64 s[40:41], s[14:15], exec
	v_mov_b32_e32 v3, s29
	v_mov_b32_e32 v5, s29
	s_cselect_b32 s40, 6, s20
	s_lshl_b32 s48, s46, 3
	s_lshl_b32 s29, s46, 10
	s_lshl_b32 s46, s46, 4
	s_and_b32 s46, s46, 48
	s_mov_b32 s21, s13
	v_or_b32_e32 v2, s28, v138
	s_or_b32 s20, s12, 1
	s_or_b32 s28, s28, s46
	s_ashr_i32 s49, s48, 31
	s_and_b32 s50, s48, 0xffffffe0
	s_lshl_b64 s[52:53], s[20:21], 6
	v_or_b32_e32 v4, s28, v104
	v_lshlrev_b64 v[2:3], s40, v[2:3]
	s_lshl_b64 s[20:21], s[48:49], 1
	s_ashr_i32 s51, s50, 31
	s_or_b32 s49, s52, s46
	v_lshlrev_b64 v[4:5], s40, v[4:5]
	s_add_i32 s41, s29, 0
	v_lshl_add_u64 v[2:3], v[2:3], 1, s[4:5]
	v_mov_b32_e32 v7, s53
	v_or_b32_e32 v6, s52, v138
	v_mov_b32_e32 v9, s53
	s_lshl_b64 s[28:29], s[50:51], 1
	v_or_b32_e32 v8, s49, v104
	v_lshl_add_u64 v[4:5], v[4:5], 1, s[0:1]
	v_lshl_add_u64 v[2:3], v[2:3], 0, s[20:21]
	v_lshlrev_b64 v[6:7], s40, v[6:7]
	v_lshlrev_b64 v[8:9], s40, v[8:9]
	v_lshl_add_u64 v[4:5], v[4:5], 0, s[28:29]
	s_add_i32 s47, s41, 0x8000
	v_lshl_add_u64 v[6:7], v[6:7], 1, s[4:5]
	v_lshl_add_u64 v[8:9], v[8:9], 1, s[0:1]
	v_lshl_add_u64 v[4:5], v[4:5], 0, v[100:101]
	s_add_i32 s48, s41, 0x2000
	v_lshl_add_u64 v[6:7], v[6:7], 0, s[20:21]
	v_lshl_add_u64 v[8:9], v[8:9], 0, s[28:29]
	v_lshl_add_u64 v[8:9], v[8:9], 0, v[100:101]
	v_lshl_add_u32 v132, v1, 2, s39
	s_waitcnt vmcnt(0)
	s_mov_b32 s49, m0
	s_mov_b32 m0, s41
	s_nop 0
	global_load_lds_dwordx4 v[2:3], off
	s_mov_b32 m0, s49
	s_nop 0
	s_mov_b32 s49, m0
	s_mov_b32 m0, s47
	s_nop 0
	global_load_lds_dwordx4 v[4:5], off
	s_mov_b32 m0, s49
	s_mov_b32 s47, m0
	s_mov_b32 m0, s48
	s_nop 0
	global_load_lds_dwordx4 v[6:7], off
	s_mov_b32 m0, s47
	s_add_i32 s47, s41, 0xa000
	s_mov_b32 s48, m0
	s_mov_b32 m0, s47
	s_nop 0
	global_load_lds_dwordx4 v[8:9], off
	s_mov_b32 m0, s48
	s_waitcnt vmcnt(2) lgkmcnt(0)
	s_barrier
	s_cmp_lt_i32 s44, 0
	s_cbranch_scc1 .LBB0_1408
	s_ashr_i32 s47, s42, 7
	s_add_i32 s42, s47, s43
	s_add_i32 s43, s47, s45
	s_add_i32 s44, s44, -2
	s_add_u32 s20, s4, s20
	s_addc_u32 s21, s5, s21
	s_add_u32 s0, s0, s28
	s_addc_u32 s1, s1, s29
	v_lshl_add_u64 v[110:111], s[0:1], 0, v[100:101]
	s_sub_i32 s0, s12, s45
	s_add_i32 s0, s0, -4
	v_add_u32_e32 v2, s38, v129
	s_lshl_b32 s1, s12, 6
	s_not_b32 s45, s12
	v_mov_b32_e32 v134, 0
	v_or_b32_e32 v112, s46, v104
	v_subrev_u32_e32 v135, s1, v2
	s_add_i32 s45, s45, s43
	v_mov_b32_e32 v133, 0xff61b1e6
	s_mov_b32 s46, 0
	v_mov_b32_e32 v136, s0
	s_mov_b32 s47, 0
	v_mov_b32_e32 v2, 0
	v_mov_b32_e32 v3, v134
	v_mov_b32_e32 v4, v134
	v_mov_b32_e32 v5, v134
	v_mov_b32_e32 v6, v134
	v_mov_b32_e32 v7, v134
	v_mov_b32_e32 v8, v134
	v_mov_b32_e32 v9, v134
	v_mov_b32_e32 v10, v134
	v_mov_b32_e32 v11, v134
	v_mov_b32_e32 v12, v134
	v_mov_b32_e32 v13, v134
	v_mov_b32_e32 v14, v134
	v_mov_b32_e32 v15, v134
	v_mov_b32_e32 v16, v134
	v_mov_b32_e32 v17, v134
	v_mov_b32_e32 v18, 0
	v_mov_b32_e32 v19, v134
	v_mov_b32_e32 v20, v134
	v_mov_b32_e32 v21, v134
	v_mov_b32_e32 v22, v134
	v_mov_b32_e32 v23, v134
	v_mov_b32_e32 v24, v134
	v_mov_b32_e32 v25, v134
	v_mov_b32_e32 v26, v134
	v_mov_b32_e32 v27, v134
	v_mov_b32_e32 v28, v134
	v_mov_b32_e32 v29, v134
	v_mov_b32_e32 v30, v134
	v_mov_b32_e32 v31, v134
	v_mov_b32_e32 v32, v134
	v_mov_b32_e32 v33, v134
	s_branch .LBB0_1395

.LBB0_1397:
	s_cmp_lt_i32 s0, s42
	s_cselect_b64 s[4:5], -1, 0
	s_cmp_gt_i32 s0, s43
	s_cselect_b64 s[0:1], -1, 0
	s_or_b64 s[0:1], s[4:5], s[0:1]
	s_and_b64 vcc, exec, s[0:1]
	s_cbranch_vccnz .LBB0_1404
	s_lshl_b32 s0, s46, 13
	v_add_u32_e32 v34, s0, v99
	v_add_u32_e32 v137, s0, v105
	ds_read_b128 v[140:143], v34
	ds_read_b128 v[144:147], v34 offset:512
	ds_read_b128 v[148:151], v34 offset:2048
	ds_read_b128 v[152:155], v34 offset:2560
	ds_read_b128 v[156:159], v34 offset:4096
	ds_read_b128 v[160:163], v34 offset:4608
	ds_read_b128 v[164:167], v34 offset:6144
	ds_read_b128 v[168:171], v34 offset:6656
	ds_read_b64_tr_b16 v[94:95], v137 offset:32768
	ds_read_b64_tr_b16 v[96:97], v137 offset:33280
	ds_read_b64_tr_b16 v[90:91], v137 offset:33792
	ds_read_b64_tr_b16 v[92:93], v137 offset:34304
	ds_read_b64_tr_b16 v[86:87], v137 offset:34816
	ds_read_b64_tr_b16 v[88:89], v137 offset:35328
	ds_read_b64_tr_b16 v[82:83], v137 offset:35840
	ds_read_b64_tr_b16 v[84:85], v137 offset:36352
	v_sub_f32_e32 v34, 0, v133
	v_cmp_eq_f32_e64 s[4:5], s30, v133
	s_nop 1
	v_cndmask_b32_e64 v34, v34, 0, s[4:5]
	v_mov_b32_e32 v35, v34
	v_mov_b32_e32 v36, v34
	v_mov_b32_e32 v37, v34
	v_mov_b32_e32 v38, v34
	v_mov_b32_e32 v39, v34
	v_mov_b32_e32 v40, v34
	v_mov_b32_e32 v41, v34
	v_mov_b32_e32 v42, v34
	v_mov_b32_e32 v43, v34
	v_mov_b32_e32 v44, v34
	v_mov_b32_e32 v45, v34
	v_mov_b32_e32 v46, v34
	v_mov_b32_e32 v47, v34
	v_mov_b32_e32 v48, v34
	v_mov_b32_e32 v49, v34
	s_waitcnt lgkmcnt(14)
	s_nop 0
	v_mfma_f32_32x32x16_bf16 v[50:65], v[140:143], v[78:81], v[34:49]
	v_mfma_f32_32x32x16_bf16 v[34:49], v[144:147], v[78:81], v[34:49]
	s_waitcnt lgkmcnt(13)
	v_mfma_f32_32x32x16_bf16 v[50:65], v[148:151], v[74:77], v[50:65]
	s_waitcnt lgkmcnt(12)
	v_mfma_f32_32x32x16_bf16 v[34:49], v[152:155], v[74:77], v[34:49]
	s_waitcnt lgkmcnt(11)
	v_mfma_f32_32x32x16_bf16 v[50:65], v[156:159], v[70:73], v[50:65]
	s_waitcnt lgkmcnt(10)
	v_mfma_f32_32x32x16_bf16 v[34:49], v[160:163], v[70:73], v[34:49]
	s_waitcnt lgkmcnt(9)
	v_mfma_f32_32x32x16_bf16 v[50:65], v[164:167], v[66:69], v[50:65]
	s_waitcnt lgkmcnt(8)
	v_mfma_f32_32x32x16_bf16 v[34:49], v[168:171], v[66:69], v[34:49]
	s_cmp_eq_u32 s45, s47
	s_cbranch_scc1 .LBB0_1400
	s_cmp_lt_i32 s47, s45
	s_cbranch_scc1 .Ldil_mask_lo
	s_cmp_eq_u32 s92, 0
	s_cbranch_scc1 .Ldil_mask_upe
	v_cmp_le_i32_e32 vcc, 32, v135
	v_cmp_le_i32_e64 s[88:89], 33, v135
	v_cmp_le_i32_e64 s[90:91], 34, v135
	s_nop 7
	s_nop 3
	v_cndmask_b32_e32 v34, v130, v34, vcc
	v_cmp_le_i32_e32 vcc, 35, v135
	v_cndmask_b32_e64 v35, v130, v35, s[88:89]
	v_cmp_le_i32_e64 s[88:89], 40, v135
	v_cndmask_b32_e64 v36, v130, v36, s[90:91]
	v_cmp_le_i32_e64 s[90:91], 41, v135
	v_cndmask_b32_e32 v37, v130, v37, vcc
	v_cmp_le_i32_e32 vcc, 42, v135
	v_cndmask_b32_e64 v38, v130, v38, s[88:89]
	v_cmp_le_i32_e64 s[88:89], 43, v135
	v_cndmask_b32_e64 v39, v130, v39, s[90:91]
	v_cmp_le_i32_e64 s[90:91], 48, v135
	v_cndmask_b32_e32 v40, v130, v40, vcc
	v_cmp_le_i32_e32 vcc, 49, v135
	v_cndmask_b32_e64 v41, v130, v41, s[88:89]
	v_cmp_le_i32_e64 s[88:89], 50, v135
	v_cndmask_b32_e64 v42, v130, v42, s[90:91]
	v_cmp_le_i32_e64 s[90:91], 51, v135
	v_cndmask_b32_e32 v43, v130, v43, vcc
	v_cmp_le_i32_e32 vcc, 56, v135
	v_cndmask_b32_e64 v44, v130, v44, s[88:89]
	v_cmp_le_i32_e64 s[88:89], 57, v135
	v_cndmask_b32_e64 v45, v130, v45, s[90:91]
	v_cmp_le_i32_e64 s[90:91], 58, v135
	v_cndmask_b32_e32 v46, v130, v46, vcc
	v_cmp_le_i32_e32 vcc, 59, v135
	v_cndmask_b32_e64 v47, v130, v47, s[88:89]
	v_cndmask_b32_e64 v48, v130, v48, s[90:91]
	v_cndmask_b32_e32 v49, v130, v49, vcc
	s_branch .LBB0_1400
.Ldil_mask_upe:
	v_cmp_le_i32_e32 vcc, 0, v135
	v_cmp_le_i32_e64 s[88:89], 1, v135
	v_cmp_le_i32_e64 s[90:91], 2, v135
	s_nop 7
	s_nop 3
	v_cndmask_b32_e32 v50, v130, v50, vcc
	v_cmp_le_i32_e32 vcc, 3, v135
	v_cndmask_b32_e64 v51, v130, v51, s[88:89]
	v_cmp_le_i32_e64 s[88:89], 8, v135
	v_cndmask_b32_e64 v52, v130, v52, s[90:91]
	v_cmp_le_i32_e64 s[90:91], 9, v135
	v_cndmask_b32_e32 v53, v130, v53, vcc
	v_cmp_le_i32_e32 vcc, 10, v135
	v_cndmask_b32_e64 v54, v130, v54, s[88:89]
	v_cmp_le_i32_e64 s[88:89], 11, v135
	v_cndmask_b32_e64 v55, v130, v55, s[90:91]
	v_cmp_le_i32_e64 s[90:91], 16, v135
	v_cndmask_b32_e32 v56, v130, v56, vcc
	v_cmp_le_i32_e32 vcc, 17, v135
	v_cndmask_b32_e64 v57, v130, v57, s[88:89]
	v_cmp_le_i32_e64 s[88:89], 18, v135
	v_cndmask_b32_e64 v58, v130, v58, s[90:91]
	v_cmp_le_i32_e64 s[90:91], 19, v135
	v_cndmask_b32_e32 v59, v130, v59, vcc
	v_cmp_le_i32_e32 vcc, 24, v135
	v_cndmask_b32_e64 v60, v130, v60, s[88:89]
	v_cmp_le_i32_e64 s[88:89], 25, v135
	v_cndmask_b32_e64 v61, v130, v61, s[90:91]
	v_cmp_le_i32_e64 s[90:91], 26, v135
	v_cndmask_b32_e32 v62, v130, v62, vcc
	v_cmp_le_i32_e32 vcc, 27, v135
	v_cndmask_b32_e64 v63, v130, v63, s[88:89]
	v_cndmask_b32_e64 v64, v130, v64, s[90:91]
	v_cndmask_b32_e32 v65, v130, v65, vcc
	v_mov_b32_e32 v34, v130
	v_mov_b32_e32 v35, v130
	v_mov_b32_e32 v36, v130
	v_mov_b32_e32 v37, v130
	v_mov_b32_e32 v38, v130
	v_mov_b32_e32 v39, v130
	v_mov_b32_e32 v40, v130
	v_mov_b32_e32 v41, v130
	v_mov_b32_e32 v42, v130
	v_mov_b32_e32 v43, v130
	v_mov_b32_e32 v44, v130
	v_mov_b32_e32 v45, v130
	v_mov_b32_e32 v46, v130
	v_mov_b32_e32 v47, v130
	v_mov_b32_e32 v48, v130
	v_mov_b32_e32 v49, v130
	s_branch .LBB0_1400
.Ldil_mask_lo:
	s_cmp_eq_u32 s92, 0
	s_cbranch_scc1 .Ldil_mask_loe
	v_add_u32_e32 v139, 0xffffff80, v135
	v_cmp_ge_i32_e32 vcc, 32, v139
	v_cmp_ge_i32_e64 s[88:89], 33, v139
	v_cmp_ge_i32_e64 s[90:91], 34, v139
	s_nop 7
	s_nop 3
	v_cndmask_b32_e32 v34, v130, v34, vcc
	v_cmp_ge_i32_e32 vcc, 35, v139
	v_cndmask_b32_e64 v35, v130, v35, s[88:89]
	v_cmp_ge_i32_e64 s[88:89], 40, v139
	v_cndmask_b32_e64 v36, v130, v36, s[90:91]
	v_cmp_ge_i32_e64 s[90:91], 41, v139
	v_cndmask_b32_e32 v37, v130, v37, vcc
	v_cmp_ge_i32_e32 vcc, 42, v139
	v_cndmask_b32_e64 v38, v130, v38, s[88:89]
	v_cmp_ge_i32_e64 s[88:89], 43, v139
	v_cndmask_b32_e64 v39, v130, v39, s[90:91]
	v_cmp_ge_i32_e64 s[90:91], 48, v139
	v_cndmask_b32_e32 v40, v130, v40, vcc
	v_cmp_ge_i32_e32 vcc, 49, v139
	v_cndmask_b32_e64 v41, v130, v41, s[88:89]
	v_cmp_ge_i32_e64 s[88:89], 50, v139
	v_cndmask_b32_e64 v42, v130, v42, s[90:91]
	v_cmp_ge_i32_e64 s[90:91], 51, v139
	v_cndmask_b32_e32 v43, v130, v43, vcc
	v_cmp_ge_i32_e32 vcc, 56, v139
	v_cndmask_b32_e64 v44, v130, v44, s[88:89]
	v_cmp_ge_i32_e64 s[88:89], 57, v139
	v_cndmask_b32_e64 v45, v130, v45, s[90:91]
	v_cmp_ge_i32_e64 s[90:91], 58, v139
	v_cndmask_b32_e32 v46, v130, v46, vcc
	v_cmp_ge_i32_e32 vcc, 59, v139
	v_cndmask_b32_e64 v47, v130, v47, s[88:89]
	v_cndmask_b32_e64 v48, v130, v48, s[90:91]
	v_cndmask_b32_e32 v49, v130, v49, vcc
	v_mov_b32_e32 v50, v130
	v_mov_b32_e32 v51, v130
	v_mov_b32_e32 v52, v130
	v_mov_b32_e32 v53, v130
	v_mov_b32_e32 v54, v130
	v_mov_b32_e32 v55, v130
	v_mov_b32_e32 v56, v130
	v_mov_b32_e32 v57, v130
	v_mov_b32_e32 v58, v130
	v_mov_b32_e32 v59, v130
	v_mov_b32_e32 v60, v130
	v_mov_b32_e32 v61, v130
	v_mov_b32_e32 v62, v130
	v_mov_b32_e32 v63, v130
	v_mov_b32_e32 v64, v130
	v_mov_b32_e32 v65, v130
	s_branch .LBB0_1400
.Ldil_mask_loe:
	v_add_u32_e32 v139, 0xffffff80, v135
	v_cmp_ge_i32_e32 vcc, 0, v139
	v_cmp_ge_i32_e64 s[88:89], 1, v139
	v_cmp_ge_i32_e64 s[90:91], 2, v139
	s_nop 7
	s_nop 3
	v_cndmask_b32_e32 v50, v130, v50, vcc
	v_cmp_ge_i32_e32 vcc, 3, v139
	v_cndmask_b32_e64 v51, v130, v51, s[88:89]
	v_cmp_ge_i32_e64 s[88:89], 8, v139
	v_cndmask_b32_e64 v52, v130, v52, s[90:91]
	v_cmp_ge_i32_e64 s[90:91], 9, v139
	v_cndmask_b32_e32 v53, v130, v53, vcc
	v_cmp_ge_i32_e32 vcc, 10, v139
	v_cndmask_b32_e64 v54, v130, v54, s[88:89]
	v_cmp_ge_i32_e64 s[88:89], 11, v139
	v_cndmask_b32_e64 v55, v130, v55, s[90:91]
	v_cmp_ge_i32_e64 s[90:91], 16, v139
	v_cndmask_b32_e32 v56, v130, v56, vcc
	v_cmp_ge_i32_e32 vcc, 17, v139
	v_cndmask_b32_e64 v57, v130, v57, s[88:89]
	v_cmp_ge_i32_e64 s[88:89], 18, v139
	v_cndmask_b32_e64 v58, v130, v58, s[90:91]
	v_cmp_ge_i32_e64 s[90:91], 19, v139
	v_cndmask_b32_e32 v59, v130, v59, vcc
	v_cmp_ge_i32_e32 vcc, 24, v139
	v_cndmask_b32_e64 v60, v130, v60, s[88:89]
	v_cmp_ge_i32_e64 s[88:89], 25, v139
	v_cndmask_b32_e64 v61, v130, v61, s[90:91]
	v_cmp_ge_i32_e64 s[90:91], 26, v139
	v_cndmask_b32_e32 v62, v130, v62, vcc
	v_cmp_ge_i32_e32 vcc, 27, v139
	v_cndmask_b32_e64 v63, v130, v63, s[88:89]
	v_cndmask_b32_e64 v64, v130, v64, s[90:91]
	v_cndmask_b32_e32 v65, v130, v65, vcc

.LBB0_1653:
	s_ashr_i32 s15, s14, 31
	s_lshl_b64 s[16:17], s[14:15], 19
	s_add_u32 s16, s80, s16
	s_addc_u32 s17, s81, s17
	s_and_b64 s[18:19], s[2:3], exec
	s_cselect_b32 s15, s17, s31
	s_cselect_b32 s47, s16, s30
	s_ashr_i32 s13, s12, 31
	s_lshl_b64 s[18:19], s[12:13], 19
	s_add_u32 s18, s23, s18
	s_addc_u32 s19, s24, s19
	s_and_b64 s[36:37], s[2:3], exec
	s_cselect_b32 s13, s19, s29
	s_cselect_b32 s48, s18, s28
	s_cmp_ge_u32 s33, 0x1000
	s_cbranch_scc1 .Lst6_skip
	s_lshl_b32 s36, s20, 12
	s_add_u32 s36, s6, s36
	s_addc_u32 s37, s7, 0
	s_and_b32 s49, s39, 1
	s_lshl_b32 s49, s49, 12
	s_add_i32 s49, s49, 0x20000
	s_add_i32 m0, s33, s49
	v_lshlrev_b32_e32 v152, 4, v0
	s_nop 0
	global_load_lds_dwordx4 v152, s[36:37]
.Lst6_skip:
	s_add_u32 s36, s30, 0x40080
	s_addc_u32 s37, s31, 0
	s_add_u32 s49, s28, 0x100
	v_mov_b32_e32 v2, 0
	v_mov_b32_e32 v3, 0
	v_mov_b64_e32 v[4:5], v[2:3]
	v_mov_b64_e32 v[6:7], v[2:3]
	v_mov_b64_e32 v[8:9], v[2:3]
	v_mov_b64_e32 v[10:11], v[2:3]
	v_mov_b64_e32 v[12:13], v[2:3]
	v_mov_b64_e32 v[14:15], v[2:3]
	v_mov_b64_e32 v[16:17], v[2:3]
	v_mov_b64_e32 v[18:19], v[2:3]
	v_mov_b64_e32 v[20:21], v[2:3]
	v_mov_b64_e32 v[22:23], v[2:3]
	v_mov_b64_e32 v[24:25], v[2:3]
	v_mov_b64_e32 v[26:27], v[2:3]
	v_mov_b64_e32 v[28:29], v[2:3]
	v_mov_b64_e32 v[30:31], v[2:3]
	v_mov_b64_e32 v[32:33], v[2:3]
	v_mov_b64_e32 v[34:35], v[2:3]
	v_mov_b64_e32 v[36:37], v[2:3]
	v_mov_b64_e32 v[38:39], v[2:3]
	v_mov_b64_e32 v[40:41], v[2:3]
	v_mov_b64_e32 v[42:43], v[2:3]
	v_mov_b64_e32 v[44:45], v[2:3]
	v_mov_b64_e32 v[46:47], v[2:3]
	v_mov_b64_e32 v[48:49], v[2:3]
	v_mov_b64_e32 v[50:51], v[2:3]
	v_mov_b64_e32 v[52:53], v[2:3]
	v_mov_b64_e32 v[54:55], v[2:3]
	v_mov_b64_e32 v[56:57], v[2:3]
	v_mov_b64_e32 v[58:59], v[2:3]
	v_mov_b64_e32 v[60:61], v[2:3]
	v_mov_b64_e32 v[62:63], v[2:3]
	v_mov_b64_e32 v[64:65], v[2:3]
	v_mov_b64_e32 v[66:67], v[2:3]
	v_mov_b64_e32 v[68:69], v[2:3]
	v_mov_b64_e32 v[70:71], v[2:3]
	v_mov_b64_e32 v[72:73], v[2:3]
	v_mov_b64_e32 v[74:75], v[2:3]
	v_mov_b64_e32 v[76:77], v[2:3]
	v_mov_b64_e32 v[78:79], v[2:3]
	v_mov_b64_e32 v[80:81], v[2:3]
	v_mov_b64_e32 v[82:83], v[2:3]
	v_mov_b64_e32 v[84:85], v[2:3]
	v_mov_b64_e32 v[86:87], v[2:3]
	v_mov_b64_e32 v[88:89], v[2:3]
	v_mov_b64_e32 v[90:91], v[2:3]
	v_mov_b64_e32 v[92:93], v[2:3]
	v_mov_b64_e32 v[94:95], v[2:3]
	v_mov_b64_e32 v[96:97], v[2:3]
	v_mov_b64_e32 v[98:99], v[2:3]
	v_mov_b64_e32 v[100:101], v[2:3]
	v_mov_b64_e32 v[102:103], v[2:3]
	v_mov_b64_e32 v[104:105], v[2:3]
	v_mov_b64_e32 v[106:107], v[2:3]
	v_mov_b64_e32 v[108:109], v[2:3]
	v_mov_b64_e32 v[110:111], v[2:3]
	v_mov_b64_e32 v[112:113], v[2:3]
	v_mov_b64_e32 v[114:115], v[2:3]
	v_mov_b64_e32 v[116:117], v[2:3]
	v_mov_b64_e32 v[118:119], v[2:3]
	v_mov_b64_e32 v[120:121], v[2:3]
	v_mov_b64_e32 v[122:123], v[2:3]
	v_mov_b64_e32 v[124:125], v[2:3]
	v_mov_b64_e32 v[126:127], v[2:3]
	v_mov_b64_e32 v[128:129], v[2:3]
	s_addc_u32 s50, s29, 0
	s_mov_b32 s51, -2

.LBB0_1657:
	v_mov_b32_e32 v254, 1.0
	s_lshl_b32 s13, s20, 8
	s_add_i32 s13, s13, s40
	v_or_b32_e32 v152, s13, v1
	s_and_b32 s36, s39, 1
	s_lshl_b32 s36, s36, 12
	s_add_i32 s36, s36, 0x20000
	s_lshl_b32 s37, s40, 4
	s_add_i32 s36, s36, s37
	v_lshl_add_u32 v212, v1, 4, s36
	v_or_b32_e32 v164, 16, v152
	v_ashrrev_i32_e32 v153, 31, v152
	v_ashrrev_i32_e32 v165, 31, v164
	v_or_b32_e32 v162, 32, v152
	v_or_b32_e32 v160, 48, v152
	v_ashrrev_i32_e32 v163, 31, v162
	v_ashrrev_i32_e32 v161, 31, v160
	ds_read_b128 v[180:183], v212
	ds_read_b128 v[184:187], v212 offset:256
	ds_read_b128 v[188:191], v212 offset:512
	ds_read_b128 v[192:195], v212 offset:768
	v_add_u32_e32 v158, 0x80, v152
	v_add_u32_e32 v156, 0x90, v152
	v_ashrrev_i32_e32 v159, 31, v158
	v_ashrrev_i32_e32 v157, 31, v156
	ds_read_b128 v[196:199], v212 offset:2048
	s_nop 0
	ds_read_b128 v[200:203], v212 offset:2304
	v_add_u32_e32 v154, 0xa0, v152
	v_ashrrev_i32_e32 v155, 31, v154
	v_add_u32_e32 v152, 0xb0, v152
	v_ashrrev_i32_e32 v153, 31, v152
	ds_read_b128 v[204:207], v212 offset:2560
	ds_read_b128 v[208:211], v212 offset:2816
	s_lshl_b32 s15, s21, 8
	s_ashr_i32 s20, s13, 4
	s_or_b32 s15, s15, s41
	s_ashr_i32 s21, s20, 31
	s_lshl_b64 s[30:31], s[20:21], 6
	s_ashr_i32 s20, s15, 5
	s_ashr_i32 s21, s20, 31
	s_add_u32 s28, s30, s20
	s_addc_u32 s29, s31, s21
	s_lshl_b64 s[28:29], s[28:29], 10
	s_waitcnt lgkmcnt(0)
	v_mov_b32_e32 v212, v181
	v_mov_b32_e32 v213, v182
	v_mov_b32_e32 v181, v183
	v_pk_add_f32 v[180:181], v[212:213], v[180:181]
	v_mov_b32_e32 v182, v185
	v_mov_b32_e32 v183, v186
	v_mov_b32_e32 v185, v187
	v_add_f32_e32 v153, v180, v181
	v_pk_add_f32 v[180:181], v[182:183], v[184:185]
	v_fmamk_f32 v153, v153, 0x3a800000, v178
	v_mov_b32_e32 v186, v189
	v_mov_b32_e32 v187, v190
	v_mov_b32_e32 v189, v191
	v_mov_b32_e32 v190, v193
	v_mov_b32_e32 v191, v194
	v_mov_b32_e32 v193, v195
	v_mov_b32_e32 v194, v197
	v_mov_b32_e32 v195, v198
	v_mov_b32_e32 v197, v199
	v_mov_b32_e32 v198, v201
	v_mov_b32_e32 v199, v202
	v_mov_b32_e32 v201, v203
	v_add_f32_e32 v155, v180, v181
	v_rsq_f32_e32 v180, v153
	v_pk_add_f32 v[182:183], v[186:187], v[188:189]
	v_pk_add_f32 v[184:185], v[190:191], v[192:193]
	v_pk_add_f32 v[186:187], v[194:195], v[196:197]
	v_pk_add_f32 v[188:189], v[198:199], v[200:201]
	v_add_f32_e32 v157, v182, v183
	v_add_f32_e32 v159, v184, v185
	v_add_f32_e32 v161, v186, v187
	v_add_f32_e32 v163, v188, v189
	v_fmamk_f32 v153, v155, 0x3a800000, v178
	v_fmamk_f32 v155, v157, 0x3a800000, v178
	v_fmamk_f32 v157, v159, 0x3a800000, v178
	v_fmamk_f32 v159, v161, 0x3a800000, v178
	v_fmamk_f32 v161, v163, 0x3a800000, v178
	v_rsq_f32_e32 v181, v155
	v_rsq_f32_e32 v155, v161
	v_mul_f32_e32 v161, 0xbfb8aa3b, v180
	v_mul_f32_e32 v122, v122, v161
	v_mov_b32_e32 v202, v205
	v_mov_b32_e32 v203, v206
	v_mov_b32_e32 v205, v207
	v_exp_f32_e32 v122, v122
	v_mul_f32_e32 v123, v123, v161
	v_mov_b32_e32 v206, v209
	v_mov_b32_e32 v207, v210
	v_mov_b32_e32 v209, v211
	v_pk_add_f32 v[190:191], v[202:203], v[204:205]
	v_exp_f32_e32 v123, v123
	v_pk_add_f32 v[192:193], v[206:207], v[208:209]
	v_add_f32_e32 v165, v190, v191
	v_add_f32_e32 v179, v192, v193
	v_fmamk_f32 v163, v165, 0x3a800000, v178
	v_mul_f32_e32 v126, v126, v161
	v_fmamk_f32 v165, v179, 0x3a800000, v178
	v_rsq_f32_e32 v179, v153
	v_rsq_f32_e32 v153, v163
	v_exp_f32_e32 v163, v126
	v_mul_f32_e32 v126, v127, v161
	v_add_f32_e32 v122, 1.0, v122
	v_exp_f32_e32 v127, v126
	v_rsq_f32_e32 v126, v165
	v_rcp_f32_e32 v165, v122
	v_add_f32_e32 v122, 1.0, v123
	v_mul_f32_e32 v123, v124, v161
	v_pk_mul_f32 v[128:129], v[128:129], v[160:161] op_sel:[0,1] op_sel_hi:[1,1]
	v_exp_f32_e32 v123, v123
	v_mul_f32_e32 v124, v125, v161
	v_exp_f32_e32 v128, v128
	v_exp_f32_e32 v129, v129
	v_exp_f32_e32 v124, v124
	v_rcp_f32_e32 v125, v122
	v_add_f32_e32 v122, 1.0, v123
	v_add_f32_e32 v163, 1.0, v163
	v_add_f32_e32 v127, 1.0, v127
	v_pk_add_f32 v[128:129], v[128:129], v[254:255] op_sel_hi:[1,0]
	v_rcp_f32_e32 v180, v122
	v_add_f32_e32 v122, 1.0, v124
	v_mul_f32_e32 v114, v114, v161
	v_rcp_f32_e32 v163, v163
	v_rcp_f32_e32 v127, v127
	v_rcp_f32_e32 v128, v128
	v_rcp_f32_e32 v129, v129
	v_rcp_f32_e32 v182, v122
	v_exp_f32_e32 v114, v114
	v_mul_f32_e32 v115, v115, v161
	v_exp_f32_e32 v115, v115
	v_cvt_pk_bf16_f32 v122, v163, v127
	v_cvt_pk_bf16_f32 v123, v128, v129
	v_cvt_pk_bf16_f32 v124, v165, v125
	v_cvt_pk_bf16_f32 v125, v180, v182
	v_lshl_add_u64 v[128:129], v[142:143], 0, s[28:29]
	v_add_f32_e32 v114, 1.0, v114
	global_store_dwordx4 v[128:129], v[122:125], off
	v_mul_f32_e32 v118, v118, v161
	v_mul_f32_e32 v119, v119, v161
	v_rcp_f32_e32 v122, v114
	v_add_f32_e32 v114, 1.0, v115
	v_mul_f32_e32 v115, v116, v161
	v_pk_mul_f32 v[120:121], v[120:121], v[160:161] op_sel:[0,1] op_sel_hi:[1,1]
	v_exp_f32_e32 v115, v115
	v_mul_f32_e32 v116, v117, v161
	v_exp_f32_e32 v118, v118
	v_exp_f32_e32 v119, v119
	v_exp_f32_e32 v120, v120
	v_exp_f32_e32 v121, v121
	v_exp_f32_e32 v116, v116
	v_rcp_f32_e32 v117, v114
	v_add_f32_e32 v114, 1.0, v115
	v_add_f32_e32 v118, 1.0, v118
	v_add_f32_e32 v119, 1.0, v119
	v_pk_add_f32 v[120:121], v[120:121], v[254:255] op_sel_hi:[1,0]
	v_rcp_f32_e32 v123, v114
	v_add_f32_e32 v114, 1.0, v116
	s_or_b32 s28, s20, 4
	v_rcp_f32_e32 v118, v118
	v_rcp_f32_e32 v119, v119
	v_rcp_f32_e32 v120, v120
	v_rcp_f32_e32 v121, v121
	v_rcp_f32_e32 v124, v114
	s_ashr_i32 s29, s28, 31
	s_add_u32 s30, s30, s28
	s_addc_u32 s31, s31, s29
	s_lshl_b64 s[30:31], s[30:31], 10
	v_cvt_pk_bf16_f32 v114, v118, v119
	v_cvt_pk_bf16_f32 v115, v120, v121
	v_cvt_pk_bf16_f32 v116, v122, v117
	v_cvt_pk_bf16_f32 v117, v123, v124
	v_lshl_add_u64 v[118:119], v[142:143], 0, s[30:31]
	global_store_dwordx4 v[118:119], v[114:117], off
	v_rsq_f32_e32 v157, v157
	v_rsq_f32_e32 v159, v159
	v_mul_f32_e32 v116, 0xbfb8aa3b, v179
	v_mul_f32_e32 v106, v106, v116
	v_exp_f32_e32 v106, v106
	v_mul_f32_e32 v107, v107, v116
	v_exp_f32_e32 v107, v107
	v_pk_mul_f32 v[110:111], v[110:111], v[116:117] op_sel_hi:[1,0]
	v_exp_f32_e32 v110, v110
	v_exp_f32_e32 v111, v111
	v_pk_mul_f32 v[112:113], v[112:113], v[116:117] op_sel_hi:[1,0]
	v_add_f32_e32 v106, 1.0, v106
	v_exp_f32_e32 v112, v112
	v_exp_f32_e32 v113, v113
	v_rcp_f32_e32 v117, v106
	v_add_f32_e32 v106, 1.0, v107
	v_pk_mul_f32 v[118:119], v[108:109], v[116:117] op_sel_hi:[1,0]
	v_exp_f32_e32 v118, v118
	v_exp_f32_e32 v119, v119
	v_pk_add_f32 v[110:111], v[110:111], v[254:255] op_sel_hi:[1,0]
	v_rcp_f32_e32 v110, v110
	v_rcp_f32_e32 v111, v111
	v_pk_add_f32 v[112:113], v[112:113], v[254:255] op_sel_hi:[1,0]
	v_rcp_f32_e32 v112, v112
	v_rcp_f32_e32 v113, v113
	v_rcp_f32_e32 v109, v106
	v_ashrrev_i32_e32 v114, 4, v164
	v_pk_add_f32 v[118:119], v[118:119], v[254:255] op_sel_hi:[1,0]
	v_rcp_f32_e32 v118, v118
	v_rcp_f32_e32 v119, v119
	v_mul_f32_e32 v98, v98, v116
	v_ashrrev_i32_e32 v115, 31, v114
	v_exp_f32_e32 v98, v98
	v_mul_f32_e32 v99, v99, v116
	v_cvt_pk_bf16_f32 v106, v110, v111
	v_lshlrev_b64 v[110:111], 6, v[114:115]
	v_exp_f32_e32 v99, v99
	v_cvt_pk_bf16_f32 v107, v112, v113
	v_lshl_add_u64 v[112:113], v[110:111], 0, s[20:21]
	v_lshlrev_b64 v[112:113], 10, v[112:113]
	v_cvt_pk_bf16_f32 v108, v117, v109
	v_cvt_pk_bf16_f32 v109, v118, v119
	v_lshl_add_u64 v[112:113], v[142:143], 0, v[112:113]
	v_mul_f32_e32 v102, v102, v116
	v_mul_f32_e32 v103, v103, v116
	v_add_f32_e32 v98, 1.0, v98
	v_exp_f32_e32 v102, v102
	v_exp_f32_e32 v103, v103
	global_store_dwordx4 v[112:113], v[106:109], off
	v_pk_mul_f32 v[104:105], v[104:105], v[116:117] op_sel_hi:[1,0]
	v_rcp_f32_e32 v106, v98
	v_add_f32_e32 v98, 1.0, v99
	v_mul_f32_e32 v99, v100, v116
	v_exp_f32_e32 v99, v99
	v_mul_f32_e32 v100, v101, v116
	v_exp_f32_e32 v104, v104
	v_exp_f32_e32 v105, v105
	v_exp_f32_e32 v100, v100
	v_add_f32_e32 v102, 1.0, v102
	v_add_f32_e32 v103, 1.0, v103
	v_rcp_f32_e32 v102, v102
	v_rcp_f32_e32 v103, v103
	v_rcp_f32_e32 v101, v98
	v_add_f32_e32 v98, 1.0, v99
	v_pk_add_f32 v[104:105], v[104:105], v[254:255] op_sel_hi:[1,0]
	v_rcp_f32_e32 v107, v98
	v_add_f32_e32 v98, 1.0, v100
	v_rcp_f32_e32 v104, v104
	v_rcp_f32_e32 v105, v105
	v_rcp_f32_e32 v108, v98
	v_cvt_pk_bf16_f32 v98, v102, v103
	v_lshl_add_u64 v[102:103], v[110:111], 0, s[28:29]
	v_lshlrev_b64 v[102:103], 10, v[102:103]
	v_cvt_pk_bf16_f32 v99, v104, v105
	v_cvt_pk_bf16_f32 v100, v106, v101
	v_cvt_pk_bf16_f32 v101, v107, v108
	v_lshl_add_u64 v[102:103], v[142:143], 0, v[102:103]
	global_store_dwordx4 v[102:103], v[98:101], off
	s_andn2_b64 vcc, exec, s[2:3]
	s_mov_b64 s[2:3], -1
	v_mul_f32_e32 v100, 0xbfb8aa3b, v181
	v_mul_f32_e32 v90, v90, v100
	v_exp_f32_e32 v90, v90
	v_mul_f32_e32 v91, v91, v100
	v_exp_f32_e32 v91, v91
	v_pk_mul_f32 v[94:95], v[94:95], v[100:101] op_sel_hi:[1,0]
	v_exp_f32_e32 v94, v94
	v_exp_f32_e32 v95, v95
	v_pk_mul_f32 v[96:97], v[96:97], v[100:101] op_sel_hi:[1,0]
	v_add_f32_e32 v90, 1.0, v90
	v_exp_f32_e32 v96, v96
	v_exp_f32_e32 v97, v97
	v_rcp_f32_e32 v101, v90
	v_add_f32_e32 v90, 1.0, v91
	v_pk_mul_f32 v[102:103], v[92:93], v[100:101] op_sel_hi:[1,0]
	v_exp_f32_e32 v102, v102
	v_exp_f32_e32 v103, v103
	v_pk_add_f32 v[94:95], v[94:95], v[254:255] op_sel_hi:[1,0]
	v_rcp_f32_e32 v94, v94
	v_rcp_f32_e32 v95, v95
	v_pk_add_f32 v[96:97], v[96:97], v[254:255] op_sel_hi:[1,0]
	v_rcp_f32_e32 v96, v96
	v_rcp_f32_e32 v97, v97
	v_rcp_f32_e32 v93, v90
	v_ashrrev_i32_e32 v98, 4, v162
	v_pk_add_f32 v[102:103], v[102:103], v[254:255] op_sel_hi:[1,0]
	v_rcp_f32_e32 v102, v102
	v_rcp_f32_e32 v103, v103
	v_mul_f32_e32 v82, v82, v100
	v_ashrrev_i32_e32 v99, 31, v98
	v_exp_f32_e32 v82, v82
	v_mul_f32_e32 v83, v83, v100
	v_cvt_pk_bf16_f32 v90, v94, v95
	v_lshlrev_b64 v[94:95], 6, v[98:99]
	v_exp_f32_e32 v83, v83
	v_cvt_pk_bf16_f32 v91, v96, v97
	v_lshl_add_u64 v[96:97], v[94:95], 0, s[20:21]
	v_lshlrev_b64 v[96:97], 10, v[96:97]
	v_cvt_pk_bf16_f32 v92, v101, v93
	v_cvt_pk_bf16_f32 v93, v102, v103
	v_lshl_add_u64 v[96:97], v[142:143], 0, v[96:97]
	v_mul_f32_e32 v86, v86, v100
	v_mul_f32_e32 v87, v87, v100
	v_add_f32_e32 v82, 1.0, v82
	v_exp_f32_e32 v86, v86
	v_exp_f32_e32 v87, v87
	global_store_dwordx4 v[96:97], v[90:93], off
	v_pk_mul_f32 v[88:89], v[88:89], v[100:101] op_sel_hi:[1,0]
	v_rcp_f32_e32 v90, v82
	v_add_f32_e32 v82, 1.0, v83
	v_mul_f32_e32 v83, v84, v100
	v_exp_f32_e32 v83, v83
	v_mul_f32_e32 v84, v85, v100
	v_exp_f32_e32 v88, v88
	v_exp_f32_e32 v89, v89
	v_exp_f32_e32 v84, v84
	v_add_f32_e32 v86, 1.0, v86
	v_add_f32_e32 v87, 1.0, v87
	v_rcp_f32_e32 v86, v86
	v_rcp_f32_e32 v87, v87
	v_rcp_f32_e32 v85, v82
	v_add_f32_e32 v82, 1.0, v83
	v_pk_add_f32 v[88:89], v[88:89], v[254:255] op_sel_hi:[1,0]
	v_rcp_f32_e32 v91, v82
	v_add_f32_e32 v82, 1.0, v84
	v_rcp_f32_e32 v88, v88
	v_rcp_f32_e32 v89, v89
	v_rcp_f32_e32 v92, v82
	v_cvt_pk_bf16_f32 v82, v86, v87
	v_lshl_add_u64 v[86:87], v[94:95], 0, s[28:29]
	v_lshlrev_b64 v[86:87], 10, v[86:87]
	v_cvt_pk_bf16_f32 v83, v88, v89
	v_cvt_pk_bf16_f32 v84, v90, v85
	v_cvt_pk_bf16_f32 v85, v91, v92
	v_lshl_add_u64 v[86:87], v[142:143], 0, v[86:87]
	global_store_dwordx4 v[86:87], v[82:85], off
	s_nop 1
	v_mul_f32_e32 v84, 0xbfb8aa3b, v157
	v_mul_f32_e32 v74, v74, v84
	v_exp_f32_e32 v74, v74
	v_mul_f32_e32 v75, v75, v84
	v_exp_f32_e32 v75, v75
	v_pk_mul_f32 v[78:79], v[78:79], v[84:85] op_sel_hi:[1,0]
	v_exp_f32_e32 v78, v78
	v_exp_f32_e32 v79, v79
	v_pk_mul_f32 v[80:81], v[80:81], v[84:85] op_sel_hi:[1,0]
	v_add_f32_e32 v74, 1.0, v74
	v_exp_f32_e32 v80, v80
	v_exp_f32_e32 v81, v81
	v_rcp_f32_e32 v85, v74
	v_add_f32_e32 v74, 1.0, v75
	v_pk_mul_f32 v[86:87], v[76:77], v[84:85] op_sel_hi:[1,0]
	v_exp_f32_e32 v86, v86
	v_exp_f32_e32 v87, v87
	v_pk_add_f32 v[78:79], v[78:79], v[254:255] op_sel_hi:[1,0]
	v_rcp_f32_e32 v78, v78
	v_rcp_f32_e32 v79, v79
	v_pk_add_f32 v[80:81], v[80:81], v[254:255] op_sel_hi:[1,0]
	v_rcp_f32_e32 v80, v80
	v_rcp_f32_e32 v81, v81
	v_rcp_f32_e32 v77, v74
	v_ashrrev_i32_e32 v82, 4, v160
	v_pk_add_f32 v[86:87], v[86:87], v[254:255] op_sel_hi:[1,0]
	v_rcp_f32_e32 v86, v86
	v_rcp_f32_e32 v87, v87
	v_mul_f32_e32 v66, v66, v84
	v_ashrrev_i32_e32 v83, 31, v82
	v_exp_f32_e32 v66, v66
	v_mul_f32_e32 v67, v67, v84
	v_cvt_pk_bf16_f32 v74, v78, v79
	v_lshlrev_b64 v[78:79], 6, v[82:83]
	v_exp_f32_e32 v67, v67
	v_cvt_pk_bf16_f32 v75, v80, v81
	v_lshl_add_u64 v[80:81], v[78:79], 0, s[20:21]
	v_lshlrev_b64 v[80:81], 10, v[80:81]
	v_cvt_pk_bf16_f32 v76, v85, v77
	v_cvt_pk_bf16_f32 v77, v86, v87
	v_lshl_add_u64 v[80:81], v[142:143], 0, v[80:81]
	v_mul_f32_e32 v70, v70, v84
	v_mul_f32_e32 v71, v71, v84
	v_add_f32_e32 v66, 1.0, v66
	v_exp_f32_e32 v70, v70
	v_exp_f32_e32 v71, v71
	global_store_dwordx4 v[80:81], v[74:77], off
	v_pk_mul_f32 v[72:73], v[72:73], v[84:85] op_sel_hi:[1,0]
	v_rcp_f32_e32 v74, v66
	v_add_f32_e32 v66, 1.0, v67
	v_mul_f32_e32 v67, v68, v84
	v_exp_f32_e32 v67, v67
	v_mul_f32_e32 v68, v69, v84
	v_exp_f32_e32 v72, v72
	v_exp_f32_e32 v73, v73
	v_exp_f32_e32 v68, v68
	v_add_f32_e32 v70, 1.0, v70
	v_add_f32_e32 v71, 1.0, v71
	v_rcp_f32_e32 v70, v70
	v_rcp_f32_e32 v71, v71
	v_rcp_f32_e32 v69, v66
	v_add_f32_e32 v66, 1.0, v67
	v_pk_add_f32 v[72:73], v[72:73], v[254:255] op_sel_hi:[1,0]
	v_rcp_f32_e32 v75, v66
	v_add_f32_e32 v66, 1.0, v68
	v_rcp_f32_e32 v72, v72
	v_rcp_f32_e32 v73, v73
	v_rcp_f32_e32 v76, v66
	v_cvt_pk_bf16_f32 v66, v70, v71
	v_lshl_add_u64 v[70:71], v[78:79], 0, s[28:29]
	v_lshlrev_b64 v[70:71], 10, v[70:71]
	v_cvt_pk_bf16_f32 v67, v72, v73
	v_cvt_pk_bf16_f32 v68, v74, v69
	v_cvt_pk_bf16_f32 v69, v75, v76
	v_lshl_add_u64 v[70:71], v[142:143], 0, v[70:71]
	global_store_dwordx4 v[70:71], v[66:69], off
	s_nop 1
	v_mul_f32_e32 v68, 0xbfb8aa3b, v159
	v_mul_f32_e32 v58, v58, v68
	v_exp_f32_e32 v58, v58
	v_mul_f32_e32 v59, v59, v68
	v_exp_f32_e32 v59, v59
	v_pk_mul_f32 v[62:63], v[62:63], v[68:69] op_sel_hi:[1,0]
	v_exp_f32_e32 v62, v62
	v_exp_f32_e32 v63, v63
	v_pk_mul_f32 v[64:65], v[64:65], v[68:69] op_sel_hi:[1,0]
	v_add_f32_e32 v58, 1.0, v58
	v_exp_f32_e32 v64, v64
	v_exp_f32_e32 v65, v65
	v_rcp_f32_e32 v69, v58
	v_add_f32_e32 v58, 1.0, v59
	v_pk_mul_f32 v[70:71], v[60:61], v[68:69] op_sel_hi:[1,0]
	v_exp_f32_e32 v70, v70
	v_exp_f32_e32 v71, v71
	v_pk_add_f32 v[62:63], v[62:63], v[254:255] op_sel_hi:[1,0]
	v_rcp_f32_e32 v62, v62
	v_rcp_f32_e32 v63, v63
	v_pk_add_f32 v[64:65], v[64:65], v[254:255] op_sel_hi:[1,0]
	v_rcp_f32_e32 v64, v64
	v_rcp_f32_e32 v65, v65
	v_rcp_f32_e32 v61, v58
	v_ashrrev_i32_e32 v66, 4, v158
	v_pk_add_f32 v[70:71], v[70:71], v[254:255] op_sel_hi:[1,0]
	v_rcp_f32_e32 v70, v70
	v_rcp_f32_e32 v71, v71
	v_mul_f32_e32 v50, v50, v68
	v_ashrrev_i32_e32 v67, 31, v66
	v_exp_f32_e32 v50, v50
	v_mul_f32_e32 v51, v51, v68
	v_cvt_pk_bf16_f32 v58, v62, v63
	v_lshlrev_b64 v[62:63], 6, v[66:67]
	v_exp_f32_e32 v51, v51
	v_cvt_pk_bf16_f32 v59, v64, v65
	v_lshl_add_u64 v[64:65], v[62:63], 0, s[20:21]
	v_lshlrev_b64 v[64:65], 10, v[64:65]
	v_cvt_pk_bf16_f32 v60, v69, v61
	v_cvt_pk_bf16_f32 v61, v70, v71
	v_lshl_add_u64 v[64:65], v[142:143], 0, v[64:65]
	v_mul_f32_e32 v54, v54, v68
	v_mul_f32_e32 v55, v55, v68
	v_add_f32_e32 v50, 1.0, v50
	v_exp_f32_e32 v54, v54
	v_exp_f32_e32 v55, v55
	global_store_dwordx4 v[64:65], v[58:61], off
	v_pk_mul_f32 v[56:57], v[56:57], v[68:69] op_sel_hi:[1,0]
	v_rcp_f32_e32 v58, v50
	v_add_f32_e32 v50, 1.0, v51
	v_mul_f32_e32 v51, v52, v68
	v_exp_f32_e32 v51, v51
	v_mul_f32_e32 v52, v53, v68
	v_exp_f32_e32 v56, v56
	v_exp_f32_e32 v57, v57
	v_exp_f32_e32 v52, v52
	v_add_f32_e32 v54, 1.0, v54
	v_add_f32_e32 v55, 1.0, v55
	v_rcp_f32_e32 v54, v54
	v_rcp_f32_e32 v55, v55
	v_rcp_f32_e32 v53, v50
	v_add_f32_e32 v50, 1.0, v51
	v_pk_add_f32 v[56:57], v[56:57], v[254:255] op_sel_hi:[1,0]
	v_rcp_f32_e32 v59, v50
	v_add_f32_e32 v50, 1.0, v52
	v_rcp_f32_e32 v56, v56
	v_rcp_f32_e32 v57, v57
	v_rcp_f32_e32 v60, v50
	v_cvt_pk_bf16_f32 v50, v54, v55
	v_lshl_add_u64 v[54:55], v[62:63], 0, s[28:29]
	v_lshlrev_b64 v[54:55], 10, v[54:55]
	v_cvt_pk_bf16_f32 v51, v56, v57
	v_cvt_pk_bf16_f32 v52, v58, v53
	v_cvt_pk_bf16_f32 v53, v59, v60
	v_lshl_add_u64 v[54:55], v[142:143], 0, v[54:55]
	global_store_dwordx4 v[54:55], v[50:53], off
	s_nop 1
	v_mul_f32_e32 v52, 0xbfb8aa3b, v155
	v_mul_f32_e32 v42, v42, v52
	v_exp_f32_e32 v42, v42
	v_mul_f32_e32 v43, v43, v52
	v_exp_f32_e32 v43, v43
	v_pk_mul_f32 v[46:47], v[46:47], v[52:53] op_sel_hi:[1,0]
	v_exp_f32_e32 v46, v46
	v_exp_f32_e32 v47, v47
	v_pk_mul_f32 v[48:49], v[48:49], v[52:53] op_sel_hi:[1,0]
	v_add_f32_e32 v42, 1.0, v42
	v_exp_f32_e32 v48, v48
	v_exp_f32_e32 v49, v49
	v_rcp_f32_e32 v53, v42
	v_add_f32_e32 v42, 1.0, v43
	v_pk_mul_f32 v[54:55], v[44:45], v[52:53] op_sel_hi:[1,0]
	v_exp_f32_e32 v54, v54
	v_exp_f32_e32 v55, v55
	v_pk_add_f32 v[46:47], v[46:47], v[254:255] op_sel_hi:[1,0]
	v_rcp_f32_e32 v46, v46
	v_rcp_f32_e32 v47, v47
	v_pk_add_f32 v[48:49], v[48:49], v[254:255] op_sel_hi:[1,0]
	v_rcp_f32_e32 v48, v48
	v_rcp_f32_e32 v49, v49
	v_rcp_f32_e32 v45, v42
	v_ashrrev_i32_e32 v50, 4, v156
	v_pk_add_f32 v[54:55], v[54:55], v[254:255] op_sel_hi:[1,0]
	v_rcp_f32_e32 v54, v54
	v_rcp_f32_e32 v55, v55
	v_mul_f32_e32 v34, v34, v52
	v_ashrrev_i32_e32 v51, 31, v50
	v_exp_f32_e32 v34, v34
	v_mul_f32_e32 v35, v35, v52
	v_cvt_pk_bf16_f32 v42, v46, v47
	v_lshlrev_b64 v[46:47], 6, v[50:51]
	v_exp_f32_e32 v35, v35
	v_cvt_pk_bf16_f32 v43, v48, v49
	v_lshl_add_u64 v[48:49], v[46:47], 0, s[20:21]
	v_lshlrev_b64 v[48:49], 10, v[48:49]
	v_cvt_pk_bf16_f32 v44, v53, v45
	v_cvt_pk_bf16_f32 v45, v54, v55
	v_lshl_add_u64 v[48:49], v[142:143], 0, v[48:49]
	v_mul_f32_e32 v38, v38, v52
	v_mul_f32_e32 v39, v39, v52
	v_add_f32_e32 v34, 1.0, v34
	v_exp_f32_e32 v38, v38
	v_exp_f32_e32 v39, v39
	global_store_dwordx4 v[48:49], v[42:45], off
	v_pk_mul_f32 v[40:41], v[40:41], v[52:53] op_sel_hi:[1,0]
	v_rcp_f32_e32 v42, v34
	v_add_f32_e32 v34, 1.0, v35
	v_mul_f32_e32 v35, v36, v52
	v_exp_f32_e32 v35, v35
	v_mul_f32_e32 v36, v37, v52
	v_exp_f32_e32 v40, v40
	v_exp_f32_e32 v41, v41
	v_exp_f32_e32 v36, v36
	v_add_f32_e32 v38, 1.0, v38
	v_add_f32_e32 v39, 1.0, v39
	v_rcp_f32_e32 v38, v38
	v_rcp_f32_e32 v39, v39
	v_rcp_f32_e32 v37, v34
	v_add_f32_e32 v34, 1.0, v35
	v_pk_add_f32 v[40:41], v[40:41], v[254:255] op_sel_hi:[1,0]
	v_rcp_f32_e32 v43, v34
	v_add_f32_e32 v34, 1.0, v36
	v_rcp_f32_e32 v40, v40
	v_rcp_f32_e32 v41, v41
	v_rcp_f32_e32 v44, v34
	v_cvt_pk_bf16_f32 v34, v38, v39
	v_lshl_add_u64 v[38:39], v[46:47], 0, s[28:29]
	v_lshlrev_b64 v[38:39], 10, v[38:39]
	v_cvt_pk_bf16_f32 v35, v40, v41
	v_cvt_pk_bf16_f32 v36, v42, v37
	v_cvt_pk_bf16_f32 v37, v43, v44
	v_lshl_add_u64 v[38:39], v[142:143], 0, v[38:39]
	global_store_dwordx4 v[38:39], v[34:37], off
	s_nop 1
	v_mul_f32_e32 v36, 0xbfb8aa3b, v153
	v_mul_f32_e32 v26, v26, v36
	v_exp_f32_e32 v26, v26
	v_mul_f32_e32 v27, v27, v36
	v_exp_f32_e32 v27, v27
	v_pk_mul_f32 v[30:31], v[30:31], v[36:37] op_sel_hi:[1,0]
	v_exp_f32_e32 v30, v30
	v_exp_f32_e32 v31, v31
	v_pk_mul_f32 v[32:33], v[32:33], v[36:37] op_sel_hi:[1,0]
	v_add_f32_e32 v26, 1.0, v26
	v_exp_f32_e32 v32, v32
	v_exp_f32_e32 v33, v33
	v_rcp_f32_e32 v37, v26
	v_add_f32_e32 v26, 1.0, v27
	v_pk_mul_f32 v[38:39], v[28:29], v[36:37] op_sel_hi:[1,0]
	v_exp_f32_e32 v38, v38
	v_exp_f32_e32 v39, v39
	v_pk_add_f32 v[30:31], v[30:31], v[254:255] op_sel_hi:[1,0]
	v_rcp_f32_e32 v30, v30
	v_rcp_f32_e32 v31, v31
	v_pk_add_f32 v[32:33], v[32:33], v[254:255] op_sel_hi:[1,0]
	v_rcp_f32_e32 v32, v32
	v_rcp_f32_e32 v33, v33
	v_rcp_f32_e32 v29, v26
	v_ashrrev_i32_e32 v34, 4, v154
	v_pk_add_f32 v[38:39], v[38:39], v[254:255] op_sel_hi:[1,0]
	v_rcp_f32_e32 v38, v38
	v_rcp_f32_e32 v39, v39
	v_mul_f32_e32 v18, v18, v36
	v_ashrrev_i32_e32 v35, 31, v34
	v_exp_f32_e32 v18, v18
	v_mul_f32_e32 v19, v19, v36
	v_cvt_pk_bf16_f32 v26, v30, v31
	v_lshlrev_b64 v[30:31], 6, v[34:35]
	v_exp_f32_e32 v19, v19
	v_cvt_pk_bf16_f32 v27, v32, v33
	v_lshl_add_u64 v[32:33], v[30:31], 0, s[20:21]
	v_lshlrev_b64 v[32:33], 10, v[32:33]
	v_cvt_pk_bf16_f32 v28, v37, v29
	v_cvt_pk_bf16_f32 v29, v38, v39
	v_lshl_add_u64 v[32:33], v[142:143], 0, v[32:33]
	v_mul_f32_e32 v22, v22, v36
	v_mul_f32_e32 v23, v23, v36
	v_add_f32_e32 v18, 1.0, v18
	v_exp_f32_e32 v22, v22
	v_exp_f32_e32 v23, v23
	global_store_dwordx4 v[32:33], v[26:29], off
	v_pk_mul_f32 v[24:25], v[24:25], v[36:37] op_sel_hi:[1,0]
	v_rcp_f32_e32 v26, v18
	v_add_f32_e32 v18, 1.0, v19
	v_mul_f32_e32 v19, v20, v36
	v_exp_f32_e32 v19, v19
	v_mul_f32_e32 v20, v21, v36
	v_exp_f32_e32 v24, v24
	v_exp_f32_e32 v25, v25
	v_exp_f32_e32 v20, v20
	v_add_f32_e32 v22, 1.0, v22
	v_add_f32_e32 v23, 1.0, v23
	v_rcp_f32_e32 v22, v22
	v_rcp_f32_e32 v23, v23
	v_rcp_f32_e32 v21, v18
	v_add_f32_e32 v18, 1.0, v19
	v_pk_add_f32 v[24:25], v[24:25], v[254:255] op_sel_hi:[1,0]
	v_rcp_f32_e32 v27, v18
	v_add_f32_e32 v18, 1.0, v20
	v_rcp_f32_e32 v24, v24
	v_rcp_f32_e32 v25, v25
	v_rcp_f32_e32 v28, v18
	v_cvt_pk_bf16_f32 v18, v22, v23
	v_lshl_add_u64 v[22:23], v[30:31], 0, s[28:29]
	v_lshlrev_b64 v[22:23], 10, v[22:23]
	v_cvt_pk_bf16_f32 v19, v24, v25
	v_cvt_pk_bf16_f32 v20, v26, v21
	v_cvt_pk_bf16_f32 v21, v27, v28
	v_lshl_add_u64 v[22:23], v[142:143], 0, v[22:23]
	global_store_dwordx4 v[22:23], v[18:21], off
	s_nop 1
	v_mul_f32_e32 v20, 0xbfb8aa3b, v126
	v_mul_f32_e32 v10, v10, v20
	v_exp_f32_e32 v10, v10
	v_mul_f32_e32 v11, v11, v20
	v_exp_f32_e32 v11, v11
	v_pk_mul_f32 v[14:15], v[14:15], v[20:21] op_sel_hi:[1,0]
	v_exp_f32_e32 v14, v14
	v_exp_f32_e32 v15, v15
	v_pk_mul_f32 v[16:17], v[16:17], v[20:21] op_sel_hi:[1,0]
	v_add_f32_e32 v10, 1.0, v10
	v_exp_f32_e32 v16, v16
	v_exp_f32_e32 v17, v17
	v_rcp_f32_e32 v21, v10
	v_add_f32_e32 v10, 1.0, v11
	v_pk_mul_f32 v[22:23], v[12:13], v[20:21] op_sel_hi:[1,0]
	v_exp_f32_e32 v22, v22
	v_exp_f32_e32 v23, v23
	v_pk_add_f32 v[14:15], v[14:15], v[254:255] op_sel_hi:[1,0]
	v_rcp_f32_e32 v14, v14
	v_rcp_f32_e32 v15, v15
	v_pk_add_f32 v[16:17], v[16:17], v[254:255] op_sel_hi:[1,0]
	v_rcp_f32_e32 v16, v16
	v_rcp_f32_e32 v17, v17
	v_rcp_f32_e32 v13, v10
	v_ashrrev_i32_e32 v18, 4, v152
	v_pk_add_f32 v[22:23], v[22:23], v[254:255] op_sel_hi:[1,0]
	v_rcp_f32_e32 v22, v22
	v_rcp_f32_e32 v23, v23
	v_mul_f32_e32 v2, v2, v20
	v_ashrrev_i32_e32 v19, 31, v18
	v_exp_f32_e32 v2, v2
	v_mul_f32_e32 v3, v3, v20
	v_cvt_pk_bf16_f32 v10, v14, v15
	v_lshlrev_b64 v[14:15], 6, v[18:19]
	v_exp_f32_e32 v3, v3
	v_cvt_pk_bf16_f32 v11, v16, v17
	v_lshl_add_u64 v[16:17], v[14:15], 0, s[20:21]
	v_lshlrev_b64 v[16:17], 10, v[16:17]
	v_cvt_pk_bf16_f32 v12, v21, v13
	v_cvt_pk_bf16_f32 v13, v22, v23
	v_lshl_add_u64 v[16:17], v[142:143], 0, v[16:17]
	v_pk_mul_f32 v[6:7], v[6:7], v[20:21] op_sel_hi:[1,0]
	v_add_f32_e32 v2, 1.0, v2
	v_exp_f32_e32 v6, v6
	v_exp_f32_e32 v7, v7
	global_store_dwordx4 v[16:17], v[10:13], off
	v_pk_mul_f32 v[8:9], v[8:9], v[20:21] op_sel_hi:[1,0]
	v_rcp_f32_e32 v10, v2
	v_add_f32_e32 v2, 1.0, v3
	v_mul_f32_e32 v3, v4, v20
	v_exp_f32_e32 v3, v3
	v_mul_f32_e32 v4, v5, v20
	v_exp_f32_e32 v8, v8
	v_exp_f32_e32 v9, v9
	v_exp_f32_e32 v4, v4
	v_pk_add_f32 v[6:7], v[6:7], v[254:255] op_sel_hi:[1,0]
	v_rcp_f32_e32 v6, v6
	v_rcp_f32_e32 v7, v7
	v_rcp_f32_e32 v5, v2
	v_add_f32_e32 v2, 1.0, v3
	v_pk_add_f32 v[8:9], v[8:9], v[254:255] op_sel_hi:[1,0]
	v_rcp_f32_e32 v11, v2
	v_add_f32_e32 v2, 1.0, v4
	v_rcp_f32_e32 v8, v8
	v_rcp_f32_e32 v9, v9
	v_rcp_f32_e32 v12, v2
	v_cvt_pk_bf16_f32 v2, v6, v7
	v_lshl_add_u64 v[6:7], v[14:15], 0, s[28:29]
	v_lshlrev_b64 v[6:7], 10, v[6:7]
	v_cvt_pk_bf16_f32 v3, v8, v9
	v_cvt_pk_bf16_f32 v4, v10, v5
	v_cvt_pk_bf16_f32 v5, v11, v12
	v_lshl_add_u64 v[6:7], v[142:143], 0, v[6:7]
	global_store_dwordx4 v[6:7], v[2:5], off
	s_cbranch_vccnz .LBB0_1646
	s_andn2_b64 vcc, exec, s[4:5]
	s_cbranch_vccnz .LBB0_1645
	s_barrier
	s_branch .LBB0_1645
